# duplicate lgkmcnt(0) waits at the six MMA segment starts removed in the four GEMM loops
# speedup vs baseline: 1.0164x; 1.0164x over previous
; #define G_STAGE(bufoff, gbase) do { _Pragma("unroll") for (int _i = 0; _i < 2; ++_i) \
;         __builtin_amdgcn_global_load_lds((const unsigned*)((const char*)(gbase) + voff[_i]), (LAS unsigned*)(lds + (bufoff) + ldsw + _i * 8192), 16, 0, 0); } while (0)
; #define G_LDA(dst, b, h) do { _Pragma("unroll") for (int m = 0; m < 4; ++m) _Pragma("unroll") for (int k = 0; k < 2; ++k) dst[m][k] = *(const LAS bf16x8*)(lds + G_SA(b, h) + aoff + m * 2048 + k * 1024); } while (0)
; #define G_LDB(dst, b, h) do { _Pragma("unroll") for (int n = 0; n < 2; ++n) _Pragma("unroll") for (int k = 0; k < 2; ++k) dst[n][k] = *(const LAS bf16x8*)(lds + G_SB(b, h) + boff + n * 2048 + k * 1024); } while (0)
; #define G_MMA(ai, bj, At, Bt) do { __builtin_amdgcn_s_setprio(1); _Pragma("unroll") for (int m = 0; m < 4; ++m) _Pragma("unroll") for (int n = 0; n < 2; ++n) _Pragma("unroll") for (int k = 0; k < 2; ++k) \
;         acc[ai][bj][m][n] = MFMA16(Bt[n][k], At[m][k], acc[ai][bj][m][n]); __builtin_amdgcn_s_setprio(0); } while (0)
; #define G_WAIT_V(n) asm volatile("s_waitcnt vmcnt(" #n ")" ::: "memory")
; #define G_WAIT_L(n) asm volatile("s_waitcnt lgkmcnt(" #n ")" ::: "memory")
; #define G_BAR __builtin_amdgcn_s_barrier()
; #define G_SCHED __builtin_amdgcn_sched_barrier(0)
; template <class Epi>
; __device__ __forceinline__ void gemm_phase(LAS unsigned char* lds, const bf16_t* Ag, const bf16_t* Btg, const int K, const int nM, const int nN, const Epi& E) {
;     ...
;             G_LDB(B0, 0, 0); G_SCHED; G_LDA(At, 0, 0); G_STAGE(G_SA(1, 1), a1 + hstep);
;             G_WAIT_L(8); G_BAR; G_WAIT_L(0); G_MMA(0, 0, At, B0); G_BAR; G_SCHED;
;             G_LDB(B1, 0, 1); G_STAGE(G_SB(0, 0), b2);
;             G_BAR; G_WAIT_L(0); G_MMA(0, 1, At, B1); G_BAR;
;             G_LDA(At, 0, 1); G_STAGE(G_SA(0, 0), a2);
;             G_BAR; G_WAIT_L(0); G_MMA(1, 0, At, B0); G_BAR; G_SCHED;
;             G_STAGE(G_SB(0, 1), b2 + hstep);
;             G_WAIT_V(6); G_BAR; G_MMA(1, 1, At, B1); G_BAR;
.LmainW_78:
	ds_read_b128 v[124:127], v217
	ds_read_b128 v[128:131], v217 offset:1024
	ds_read_b128 v[132:135], v217 offset:2048
	ds_read_b128 v[136:139], v217 offset:3072
	s_add_i32 m0, s58, 0xc000
	ds_read_b128 v[140:143], v186
	ds_read_b128 v[148:151], v186 offset:1024
	ds_read_b128 v[152:155], v186 offset:2048
	ds_read_b128 v[156:159], v186 offset:3072
	ds_read_b128 v[188:191], v186 offset:4096
	ds_read_b128 v[192:195], v186 offset:5120
	ds_read_b128 v[222:225], v186 offset:6144
	global_load_lds_dwordx4 v170, s[50:51]
	s_add_i32 m0, s58, 0xe000
	ds_read_b128 v[226:229], v186 offset:7168
	global_load_lds_dwordx4 v168, s[50:51]
	s_waitcnt lgkmcnt(8)
	s_barrier
	s_waitcnt lgkmcnt(0)
	v_mfma_f32_16x16x32_bf16 v[164:167], v[124:127], v[140:143], v[164:167]
	v_mfma_f32_16x16x32_bf16 v[160:163], v[132:135], v[140:143], v[160:163]
	v_mfma_f32_16x16x32_bf16 v[116:119], v[124:127], v[152:155], v[116:119]
	v_mfma_f32_16x16x32_bf16 v[112:115], v[132:135], v[152:155], v[112:115]
	v_mfma_f32_16x16x32_bf16 v[100:103], v[124:127], v[188:191], v[100:103]
	v_mfma_f32_16x16x32_bf16 v[96:99], v[132:135], v[188:191], v[96:99]
	v_mfma_f32_16x16x32_bf16 v[84:87], v[124:127], v[222:225], v[84:87]
	v_mfma_f32_16x16x32_bf16 v[80:83], v[132:135], v[222:225], v[80:83]
	v_mfma_f32_16x16x32_bf16 v[164:167], v[128:131], v[148:151], v[164:167]
	v_mfma_f32_16x16x32_bf16 v[160:163], v[136:139], v[148:151], v[160:163]
	v_mfma_f32_16x16x32_bf16 v[116:119], v[128:131], v[156:159], v[116:119]
	v_mfma_f32_16x16x32_bf16 v[112:115], v[136:139], v[156:159], v[112:115]
	v_mfma_f32_16x16x32_bf16 v[100:103], v[128:131], v[192:195], v[100:103]
	v_mfma_f32_16x16x32_bf16 v[96:99], v[136:139], v[192:195], v[96:99]
	v_mfma_f32_16x16x32_bf16 v[84:87], v[128:131], v[226:229], v[84:87]
	v_mfma_f32_16x16x32_bf16 v[80:83], v[136:139], v[226:229], v[80:83]
	s_barrier
	ds_read_b128 v[230:233], v217 offset:16384
	ds_read_b128 v[234:237], v217 offset:17408
	s_add_i32 m0, s57, 0x10000
	ds_read_b128 v[238:241], v217 offset:18432
	global_load_lds_dwordx4 v0, s[52:53]
	s_add_i32 m0, s57, 0x12000
	ds_read_b128 v[242:245], v217 offset:19456
	global_load_lds_dwordx4 v2, s[52:53]
	s_barrier
	s_waitcnt lgkmcnt(0)
	v_mfma_f32_16x16x32_bf16 v[144:147], v[230:233], v[140:143], v[144:147]
	v_mfma_f32_16x16x32_bf16 v[120:123], v[238:241], v[140:143], v[120:123]
	v_mfma_f32_16x16x32_bf16 v[108:111], v[230:233], v[152:155], v[108:111]
	v_mfma_f32_16x16x32_bf16 v[104:107], v[238:241], v[152:155], v[104:107]
	v_mfma_f32_16x16x32_bf16 v[92:95], v[230:233], v[188:191], v[92:95]
	v_mfma_f32_16x16x32_bf16 v[88:91], v[238:241], v[188:191], v[88:91]
	v_mfma_f32_16x16x32_bf16 v[76:79], v[230:233], v[222:225], v[76:79]
	v_mfma_f32_16x16x32_bf16 v[72:75], v[238:241], v[222:225], v[72:75]
	v_mfma_f32_16x16x32_bf16 v[144:147], v[234:237], v[148:151], v[144:147]
	v_mfma_f32_16x16x32_bf16 v[120:123], v[242:245], v[148:151], v[120:123]
	v_mfma_f32_16x16x32_bf16 v[108:111], v[234:237], v[156:159], v[108:111]
	v_mfma_f32_16x16x32_bf16 v[104:107], v[242:245], v[156:159], v[104:107]
	v_mfma_f32_16x16x32_bf16 v[92:95], v[234:237], v[192:195], v[92:95]
	v_mfma_f32_16x16x32_bf16 v[88:91], v[242:245], v[192:195], v[88:91]
	v_mfma_f32_16x16x32_bf16 v[76:79], v[234:237], v[226:229], v[76:79]
	v_mfma_f32_16x16x32_bf16 v[72:75], v[242:245], v[226:229], v[72:75]
	s_mov_b32 m0, s58
	s_barrier
	ds_read_b128 v[140:143], v186 offset:16384
	ds_read_b128 v[148:151], v186 offset:17408
	ds_read_b128 v[152:155], v186 offset:18432
	ds_read_b128 v[156:159], v186 offset:19456
	ds_read_b128 v[188:191], v186 offset:20480
	ds_read_b128 v[192:195], v186 offset:21504
	ds_read_b128 v[222:225], v186 offset:22528
	global_load_lds_dwordx4 v0, s[54:55]
	s_mov_b32 m0, s59
	ds_read_b128 v[226:229], v186 offset:23552
	global_load_lds_dwordx4 v2, s[54:55]
	s_barrier
	s_waitcnt lgkmcnt(0)
	v_mfma_f32_16x16x32_bf16 v[60:63], v[124:127], v[140:143], v[60:63]
	v_mfma_f32_16x16x32_bf16 v[56:59], v[132:135], v[140:143], v[56:59]
	v_mfma_f32_16x16x32_bf16 v[44:47], v[124:127], v[152:155], v[44:47]
	v_mfma_f32_16x16x32_bf16 v[40:43], v[132:135], v[152:155], v[40:43]
	v_mfma_f32_16x16x32_bf16 v[28:31], v[124:127], v[188:191], v[28:31]
	v_mfma_f32_16x16x32_bf16 v[24:27], v[132:135], v[188:191], v[24:27]
	v_mfma_f32_16x16x32_bf16 v[12:15], v[124:127], v[222:225], v[12:15]
	v_mfma_f32_16x16x32_bf16 v[8:11], v[132:135], v[222:225], v[8:11]
	v_mfma_f32_16x16x32_bf16 v[60:63], v[128:131], v[148:151], v[60:63]
	v_mfma_f32_16x16x32_bf16 v[56:59], v[136:139], v[148:151], v[56:59]
	v_mfma_f32_16x16x32_bf16 v[44:47], v[128:131], v[156:159], v[44:47]
	v_mfma_f32_16x16x32_bf16 v[40:43], v[136:139], v[156:159], v[40:43]
	v_mfma_f32_16x16x32_bf16 v[28:31], v[128:131], v[192:195], v[28:31]
	v_mfma_f32_16x16x32_bf16 v[24:27], v[136:139], v[192:195], v[24:27]
	v_mfma_f32_16x16x32_bf16 v[12:15], v[128:131], v[226:229], v[12:15]
	v_mfma_f32_16x16x32_bf16 v[8:11], v[136:139], v[226:229], v[8:11]
	s_barrier
	s_add_i32 m0, s57, 0x14000
	s_add_u32 s74, s52, 0x40000
	s_addc_u32 s75, s53, 0
	global_load_lds_dwordx4 v0, s[74:75]
	s_add_i32 m0, s57, 0x16000
	s_add_u32 s54, s54, 0x40000
	s_addc_u32 s55, s55, 0
	global_load_lds_dwordx4 v2, s[74:75]
	s_waitcnt vmcnt(6)
	s_barrier
; #define G_STAGE(bufoff, gbase) do { _Pragma("unroll") for (int _i = 0; _i < 2; ++_i) \
;         __builtin_amdgcn_global_load_lds((const unsigned*)((const char*)(gbase) + voff[_i]), (LAS unsigned*)(lds + (bufoff) + ldsw + _i * 8192), 16, 0, 0); } while (0)
; #define G_LDA(dst, b, h) do { _Pragma("unroll") for (int m = 0; m < 4; ++m) _Pragma("unroll") for (int k = 0; k < 2; ++k) dst[m][k] = *(const LAS bf16x8*)(lds + G_SA(b, h) + aoff + m * 2048 + k * 1024); } while (0)
; #define G_LDB(dst, b, h) do { _Pragma("unroll") for (int n = 0; n < 2; ++n) _Pragma("unroll") for (int k = 0; k < 2; ++k) dst[n][k] = *(const LAS bf16x8*)(lds + G_SB(b, h) + boff + n * 2048 + k * 1024); } while (0)
; #define G_MMA(ai, bj, At, Bt) do { __builtin_amdgcn_s_setprio(1); _Pragma("unroll") for (int m = 0; m < 4; ++m) _Pragma("unroll") for (int n = 0; n < 2; ++n) _Pragma("unroll") for (int k = 0; k < 2; ++k) \
;         acc[ai][bj][m][n] = MFMA16(Bt[n][k], At[m][k], acc[ai][bj][m][n]); __builtin_amdgcn_s_setprio(0); } while (0)
; #define G_WAIT_V(n) asm volatile("s_waitcnt vmcnt(" #n ")" ::: "memory")
; #define G_WAIT_L(n) asm volatile("s_waitcnt lgkmcnt(" #n ")" ::: "memory")
; #define G_BAR __builtin_amdgcn_s_barrier()
; #define G_SCHED __builtin_amdgcn_sched_barrier(0)
; template <class Epi>
; __device__ __forceinline__ void gemm_phase(LAS unsigned char* lds, const bf16_t* Ag, const bf16_t* Btg, const int K, const int nM, const int nN, const Epi& E) {
;     ...
;             const char* a1 = cA + (size_t)(t + 1) * kstep;
;             const char* a2 = last ? nA : cA + (size_t)(t + 2) * kstep; const char* b2 = last ? nB : cB + (size_t)(t + 2) * kstep;
;             const char* a3 = a2 + kstep; const char* b3 = b2 + kstep;
;     ...
;             G_WAIT_V(6); G_BAR; G_MMA(1, 1, At, B1); G_BAR;
;             G_LDB(B0, 1, 0); G_SCHED; G_LDA(At, 1, 0); G_STAGE(G_SA(0, 1), a2 + hstep);
;             G_WAIT_L(8); G_BAR; G_WAIT_L(0); G_MMA(0, 0, At, B0); G_BAR; G_SCHED;
;             G_LDB(B1, 1, 1); G_STAGE(G_SB(1, 0), b3);
;             G_BAR; G_WAIT_L(0); G_MMA(0, 1, At, B1); G_BAR;
;             G_LDA(At, 1, 1); G_STAGE(G_SA(1, 0), a3);
;             G_BAR; G_WAIT_L(0); G_MMA(1, 0, At, B0); G_BAR; G_SCHED;
;             G_STAGE(G_SB(1, 1), b3 + hstep);
;             G_WAIT_V(6); G_BAR; G_MMA(1, 1, At, B1); G_BAR;
	v_mfma_f32_16x16x32_bf16 v[68:71], v[230:233], v[140:143], v[68:71]
	v_mfma_f32_16x16x32_bf16 v[64:67], v[238:241], v[140:143], v[64:67]
	v_mfma_f32_16x16x32_bf16 v[52:55], v[230:233], v[152:155], v[52:55]
	v_mfma_f32_16x16x32_bf16 v[48:51], v[238:241], v[152:155], v[48:51]
	v_mfma_f32_16x16x32_bf16 v[36:39], v[230:233], v[188:191], v[36:39]
	v_mfma_f32_16x16x32_bf16 v[32:35], v[238:241], v[188:191], v[32:35]
	v_mfma_f32_16x16x32_bf16 v[20:23], v[230:233], v[222:225], v[20:23]
	v_mfma_f32_16x16x32_bf16 v[16:19], v[238:241], v[222:225], v[16:19]
	v_mfma_f32_16x16x32_bf16 v[68:71], v[234:237], v[148:151], v[68:71]
	v_mfma_f32_16x16x32_bf16 v[64:67], v[242:245], v[148:151], v[64:67]
	v_mfma_f32_16x16x32_bf16 v[52:55], v[234:237], v[156:159], v[52:55]
	v_mfma_f32_16x16x32_bf16 v[48:51], v[242:245], v[156:159], v[48:51]
	v_mfma_f32_16x16x32_bf16 v[36:39], v[234:237], v[192:195], v[36:39]
	v_mfma_f32_16x16x32_bf16 v[32:35], v[242:245], v[192:195], v[32:35]
	v_mfma_f32_16x16x32_bf16 v[20:23], v[234:237], v[226:229], v[20:23]
	v_mfma_f32_16x16x32_bf16 v[16:19], v[242:245], v[226:229], v[16:19]
	s_barrier
	ds_read_b128 v[124:127], v217 offset:32768
	ds_read_b128 v[128:131], v217 offset:33792
	ds_read_b128 v[132:135], v217 offset:34816
	ds_read_b128 v[136:139], v217 offset:35840
	s_mov_b32 m0, s60
	ds_read_b128 v[140:143], v186 offset:32768
	ds_read_b128 v[148:151], v186 offset:33792
	ds_read_b128 v[152:155], v186 offset:34816
	ds_read_b128 v[156:159], v186 offset:35840
	ds_read_b128 v[188:191], v186 offset:36864
	ds_read_b128 v[192:195], v186 offset:37888
	ds_read_b128 v[222:225], v186 offset:38912
	global_load_lds_dwordx4 v0, s[54:55]
	s_mov_b32 m0, s61
	ds_read_b128 v[226:229], v186 offset:39936
	global_load_lds_dwordx4 v2, s[54:55]
	s_waitcnt lgkmcnt(8)
	s_barrier
	s_waitcnt lgkmcnt(0)
	v_mfma_f32_16x16x32_bf16 v[164:167], v[124:127], v[140:143], v[164:167]
	v_mfma_f32_16x16x32_bf16 v[160:163], v[132:135], v[140:143], v[160:163]
	v_mfma_f32_16x16x32_bf16 v[116:119], v[124:127], v[152:155], v[116:119]
	v_mfma_f32_16x16x32_bf16 v[112:115], v[132:135], v[152:155], v[112:115]
	v_mfma_f32_16x16x32_bf16 v[100:103], v[124:127], v[188:191], v[100:103]
	v_mfma_f32_16x16x32_bf16 v[96:99], v[132:135], v[188:191], v[96:99]
	v_mfma_f32_16x16x32_bf16 v[84:87], v[124:127], v[222:225], v[84:87]
	v_mfma_f32_16x16x32_bf16 v[80:83], v[132:135], v[222:225], v[80:83]
	v_mfma_f32_16x16x32_bf16 v[164:167], v[128:131], v[148:151], v[164:167]
	v_mfma_f32_16x16x32_bf16 v[160:163], v[136:139], v[148:151], v[160:163]
	v_mfma_f32_16x16x32_bf16 v[116:119], v[128:131], v[156:159], v[116:119]
	v_mfma_f32_16x16x32_bf16 v[112:115], v[136:139], v[156:159], v[112:115]
	v_mfma_f32_16x16x32_bf16 v[100:103], v[128:131], v[192:195], v[100:103]
	v_mfma_f32_16x16x32_bf16 v[96:99], v[136:139], v[192:195], v[96:99]
	v_mfma_f32_16x16x32_bf16 v[84:87], v[128:131], v[226:229], v[84:87]
	v_mfma_f32_16x16x32_bf16 v[80:83], v[136:139], v[226:229], v[80:83]
	s_barrier
	s_add_i32 m0, s57, 0x18000
	ds_read_b128 v[230:233], v217 offset:49152
	ds_read_b128 v[234:237], v217 offset:50176
	ds_read_b128 v[238:241], v217 offset:51200
	s_add_u32 s98, s52, 0x80
	s_addc_u32 s99, s53, 0
	global_load_lds_dwordx4 v0, s[98:99]
	s_add_i32 m0, s57, 0x1a000
	ds_read_b128 v[242:245], v217 offset:52224
	global_load_lds_dwordx4 v2, s[98:99]
	s_barrier
	s_waitcnt lgkmcnt(0)
	v_mfma_f32_16x16x32_bf16 v[144:147], v[230:233], v[140:143], v[144:147]
	v_mfma_f32_16x16x32_bf16 v[120:123], v[238:241], v[140:143], v[120:123]
	v_mfma_f32_16x16x32_bf16 v[108:111], v[230:233], v[152:155], v[108:111]
	v_mfma_f32_16x16x32_bf16 v[104:107], v[238:241], v[152:155], v[104:107]
	v_mfma_f32_16x16x32_bf16 v[92:95], v[230:233], v[188:191], v[92:95]
	v_mfma_f32_16x16x32_bf16 v[88:91], v[238:241], v[188:191], v[88:91]
	v_mfma_f32_16x16x32_bf16 v[76:79], v[230:233], v[222:225], v[76:79]
	v_mfma_f32_16x16x32_bf16 v[72:75], v[238:241], v[222:225], v[72:75]
	v_mfma_f32_16x16x32_bf16 v[144:147], v[234:237], v[148:151], v[144:147]
	v_mfma_f32_16x16x32_bf16 v[120:123], v[242:245], v[148:151], v[120:123]
	v_mfma_f32_16x16x32_bf16 v[108:111], v[234:237], v[156:159], v[108:111]
	v_mfma_f32_16x16x32_bf16 v[104:107], v[242:245], v[156:159], v[104:107]
	v_mfma_f32_16x16x32_bf16 v[92:95], v[234:237], v[192:195], v[92:95]
	v_mfma_f32_16x16x32_bf16 v[88:91], v[242:245], v[192:195], v[88:91]
	v_mfma_f32_16x16x32_bf16 v[76:79], v[234:237], v[226:229], v[76:79]
	v_mfma_f32_16x16x32_bf16 v[72:75], v[242:245], v[226:229], v[72:75]
	s_mov_b32 m0, s62
	s_barrier
	ds_read_b128 v[140:143], v186 offset:49152
	ds_read_b128 v[148:151], v186 offset:50176
	ds_read_b128 v[152:155], v186 offset:51200
	ds_read_b128 v[156:159], v186 offset:52224
	ds_read_b128 v[188:191], v186 offset:53248
	ds_read_b128 v[192:195], v186 offset:54272
	ds_read_b128 v[222:225], v186 offset:55296
	s_add_u32 s98, s54, 0xfffc0080
	s_addc_u32 s99, s55, -1
	global_load_lds_dwordx4 v0, s[98:99]
	s_mov_b32 m0, s63
	ds_read_b128 v[226:229], v186 offset:56320
	global_load_lds_dwordx4 v2, s[98:99]
	s_barrier
	s_waitcnt lgkmcnt(0)
	v_mfma_f32_16x16x32_bf16 v[60:63], v[124:127], v[140:143], v[60:63]
	v_mfma_f32_16x16x32_bf16 v[56:59], v[132:135], v[140:143], v[56:59]
	v_mfma_f32_16x16x32_bf16 v[44:47], v[124:127], v[152:155], v[44:47]
	v_mfma_f32_16x16x32_bf16 v[40:43], v[132:135], v[152:155], v[40:43]
	v_mfma_f32_16x16x32_bf16 v[28:31], v[124:127], v[188:191], v[28:31]
	v_mfma_f32_16x16x32_bf16 v[24:27], v[132:135], v[188:191], v[24:27]
	v_mfma_f32_16x16x32_bf16 v[12:15], v[124:127], v[222:225], v[12:15]
	v_mfma_f32_16x16x32_bf16 v[8:11], v[132:135], v[222:225], v[8:11]
	v_mfma_f32_16x16x32_bf16 v[60:63], v[128:131], v[148:151], v[60:63]
	v_mfma_f32_16x16x32_bf16 v[56:59], v[136:139], v[148:151], v[56:59]
	v_mfma_f32_16x16x32_bf16 v[44:47], v[128:131], v[156:159], v[44:47]
	v_mfma_f32_16x16x32_bf16 v[40:43], v[136:139], v[156:159], v[40:43]
	v_mfma_f32_16x16x32_bf16 v[28:31], v[128:131], v[192:195], v[28:31]
	v_mfma_f32_16x16x32_bf16 v[24:27], v[136:139], v[192:195], v[24:27]
	v_mfma_f32_16x16x32_bf16 v[12:15], v[128:131], v[226:229], v[12:15]
	v_mfma_f32_16x16x32_bf16 v[8:11], v[136:139], v[226:229], v[8:11]
	s_barrier
	s_add_i32 m0, s57, 0x1c000
	s_add_u32 s52, s52, 0x40080
	s_addc_u32 s53, s53, 0
	global_load_lds_dwordx4 v0, s[52:53]
	s_add_i32 m0, s57, 0x1e000
	s_add_i32 s73, s73, 2
	global_load_lds_dwordx4 v2, s[52:53]
	s_add_u32 s71, s71, 0x100
	s_addc_u32 s72, s72, 0
	s_add_u32 s50, s50, 0x100
	s_addc_u32 s51, s51, 0
	s_cmp_gt_u32 s73, 13
	s_cbranch_scc1 .LrotX_78
	s_cmp_lg_u32 s73, 12
	s_cselect_b64 s[52:53], -1, 0
	s_add_u32 s12, s50, 0xfffc0080
	s_addc_u32 s26, s51, -1
	s_and_b64 s[52:53], s[52:53], exec
	s_cselect_b32 s55, s26, s43
	s_cselect_b32 s54, s12, s42
	s_cselect_b32 s53, s72, s15
	s_cselect_b32 s52, s71, s69

; #define G_STAGE(bufoff, gbase) do { _Pragma("unroll") for (int _i = 0; _i < 2; ++_i) \
;         __builtin_amdgcn_global_load_lds((const unsigned*)((const char*)(gbase) + voff[_i]), (LAS unsigned*)(lds + (bufoff) + ldsw + _i * 8192), 16, 0, 0); } while (0)
; #define G_LDA(dst, b, h) do { _Pragma("unroll") for (int m = 0; m < 4; ++m) _Pragma("unroll") for (int k = 0; k < 2; ++k) dst[m][k] = *(const LAS bf16x8*)(lds + G_SA(b, h) + aoff + m * 2048 + k * 1024); } while (0)
; #define G_LDB(dst, b, h) do { _Pragma("unroll") for (int n = 0; n < 2; ++n) _Pragma("unroll") for (int k = 0; k < 2; ++k) dst[n][k] = *(const LAS bf16x8*)(lds + G_SB(b, h) + boff + n * 2048 + k * 1024); } while (0)
; #define G_MMA(ai, bj, At, Bt) do { __builtin_amdgcn_s_setprio(1); _Pragma("unroll") for (int m = 0; m < 4; ++m) _Pragma("unroll") for (int n = 0; n < 2; ++n) _Pragma("unroll") for (int k = 0; k < 2; ++k) \
;         acc[ai][bj][m][n] = MFMA16(Bt[n][k], At[m][k], acc[ai][bj][m][n]); __builtin_amdgcn_s_setprio(0); } while (0)
; #define G_WAIT_V(n) asm volatile("s_waitcnt vmcnt(" #n ")" ::: "memory")
; #define G_WAIT_L(n) asm volatile("s_waitcnt lgkmcnt(" #n ")" ::: "memory")
; #define G_BAR __builtin_amdgcn_s_barrier()
; #define G_SCHED __builtin_amdgcn_sched_barrier(0)
; template <class Epi>
; __device__ __forceinline__ void gemm_phase(LAS unsigned char* lds, const bf16_t* Ag, const bf16_t* Btg, const int K, const int nM, const int nN, const Epi& E) {
;     ...
;             G_LDB(B0, 0, 0); G_SCHED; G_LDA(At, 0, 0); G_STAGE(G_SA(1, 1), a1 + hstep);
;             G_WAIT_L(8); G_BAR; G_WAIT_L(0); G_MMA(0, 0, At, B0); G_BAR; G_SCHED;
;             G_LDB(B1, 0, 1); G_STAGE(G_SB(0, 0), b2);
;             G_BAR; G_WAIT_L(0); G_MMA(0, 1, At, B1); G_BAR;
;             G_LDA(At, 0, 1); G_STAGE(G_SA(0, 0), a2);
;             G_BAR; G_WAIT_L(0); G_MMA(1, 0, At, B0); G_BAR; G_SCHED;
;             G_STAGE(G_SB(0, 1), b2 + hstep);
;             G_WAIT_V(6); G_BAR; G_MMA(1, 1, At, B1); G_BAR;
.LmainW_153:
	ds_read_b128 v[144:147], v217
	ds_read_b128 v[148:151], v217 offset:1024
	ds_read_b128 v[152:155], v217 offset:2048
	ds_read_b128 v[156:159], v217 offset:3072
	s_add_i32 m0, s72, 0xc000
	ds_read_b128 v[160:163], v230
	ds_read_b128 v[164:167], v230 offset:1024
	ds_read_b128 v[168:171], v230 offset:2048
	ds_read_b128 v[172:175], v230 offset:3072
	ds_read_b128 v[180:183], v230 offset:4096
	ds_read_b128 v[184:187], v230 offset:5120
	ds_read_b128 v[188:191], v230 offset:6144
	global_load_lds_dwordx4 v138, s[64:65]
	s_add_i32 m0, s72, 0xe000
	ds_read_b128 v[192:195], v230 offset:7168
	global_load_lds_dwordx4 v136, s[64:65]
	s_waitcnt lgkmcnt(8)
	s_barrier
	s_waitcnt lgkmcnt(0)
	v_mfma_f32_16x16x32_bf16 v[132:135], v[144:147], v[160:163], v[132:135]
	v_mfma_f32_16x16x32_bf16 v[128:131], v[152:155], v[160:163], v[128:131]
	v_mfma_f32_16x16x32_bf16 v[116:119], v[144:147], v[168:171], v[116:119]
	v_mfma_f32_16x16x32_bf16 v[112:115], v[152:155], v[168:171], v[112:115]
	v_mfma_f32_16x16x32_bf16 v[100:103], v[144:147], v[180:183], v[100:103]
	v_mfma_f32_16x16x32_bf16 v[96:99], v[152:155], v[180:183], v[96:99]
	v_mfma_f32_16x16x32_bf16 v[84:87], v[144:147], v[188:191], v[84:87]
	v_mfma_f32_16x16x32_bf16 v[80:83], v[152:155], v[188:191], v[80:83]
	v_mfma_f32_16x16x32_bf16 v[132:135], v[148:151], v[164:167], v[132:135]
	v_mfma_f32_16x16x32_bf16 v[128:131], v[156:159], v[164:167], v[128:131]
	v_mfma_f32_16x16x32_bf16 v[116:119], v[148:151], v[172:175], v[116:119]
	v_mfma_f32_16x16x32_bf16 v[112:115], v[156:159], v[172:175], v[112:115]
	v_mfma_f32_16x16x32_bf16 v[100:103], v[148:151], v[184:187], v[100:103]
	v_mfma_f32_16x16x32_bf16 v[96:99], v[156:159], v[184:187], v[96:99]
	v_mfma_f32_16x16x32_bf16 v[84:87], v[148:151], v[192:195], v[84:87]
	v_mfma_f32_16x16x32_bf16 v[80:83], v[156:159], v[192:195], v[80:83]
	s_barrier
	s_add_i32 m0, s21, 0x10000
	ds_read_b128 v[232:235], v217 offset:16384
	ds_read_b128 v[236:239], v217 offset:17408
	ds_read_b128 v[240:243], v217 offset:18432
	global_load_lds_dwordx4 v0, s[68:69]
	s_add_i32 m0, s21, 0x12000
	ds_read_b128 v[244:247], v217 offset:19456
	global_load_lds_dwordx4 v2, s[68:69]
	s_barrier
	s_waitcnt lgkmcnt(0)
	v_mfma_f32_16x16x32_bf16 v[124:127], v[232:235], v[160:163], v[124:127]
	v_mfma_f32_16x16x32_bf16 v[120:123], v[240:243], v[160:163], v[120:123]
	v_mfma_f32_16x16x32_bf16 v[108:111], v[232:235], v[168:171], v[108:111]
	v_mfma_f32_16x16x32_bf16 v[104:107], v[240:243], v[168:171], v[104:107]
	v_mfma_f32_16x16x32_bf16 v[92:95], v[232:235], v[180:183], v[92:95]
	v_mfma_f32_16x16x32_bf16 v[88:91], v[240:243], v[180:183], v[88:91]
	v_mfma_f32_16x16x32_bf16 v[76:79], v[232:235], v[188:191], v[76:79]
	v_mfma_f32_16x16x32_bf16 v[72:75], v[240:243], v[188:191], v[72:75]
	v_mfma_f32_16x16x32_bf16 v[124:127], v[236:239], v[164:167], v[124:127]
	v_mfma_f32_16x16x32_bf16 v[120:123], v[244:247], v[164:167], v[120:123]
	v_mfma_f32_16x16x32_bf16 v[108:111], v[236:239], v[172:175], v[108:111]
	v_mfma_f32_16x16x32_bf16 v[104:107], v[244:247], v[172:175], v[104:107]
	v_mfma_f32_16x16x32_bf16 v[92:95], v[236:239], v[184:187], v[92:95]
	v_mfma_f32_16x16x32_bf16 v[88:91], v[244:247], v[184:187], v[88:91]
	v_mfma_f32_16x16x32_bf16 v[76:79], v[236:239], v[192:195], v[76:79]
	v_mfma_f32_16x16x32_bf16 v[72:75], v[244:247], v[192:195], v[72:75]
	s_mov_b32 m0, s72
	s_barrier
	ds_read_b128 v[160:163], v230 offset:16384
	ds_read_b128 v[164:167], v230 offset:17408
	ds_read_b128 v[168:171], v230 offset:18432
	ds_read_b128 v[172:175], v230 offset:19456
	ds_read_b128 v[180:183], v230 offset:20480
	ds_read_b128 v[184:187], v230 offset:21504
	ds_read_b128 v[188:191], v230 offset:22528
	global_load_lds_dwordx4 v0, s[70:71]
	s_mov_b32 m0, s73
	ds_read_b128 v[192:195], v230 offset:23552
	global_load_lds_dwordx4 v2, s[70:71]
	s_barrier
	s_waitcnt lgkmcnt(0)
	v_mfma_f32_16x16x32_bf16 v[68:71], v[144:147], v[160:163], v[68:71]
	v_mfma_f32_16x16x32_bf16 v[64:67], v[152:155], v[160:163], v[64:67]
	v_mfma_f32_16x16x32_bf16 v[52:55], v[144:147], v[168:171], v[52:55]
	v_mfma_f32_16x16x32_bf16 v[48:51], v[152:155], v[168:171], v[48:51]
	v_mfma_f32_16x16x32_bf16 v[36:39], v[144:147], v[180:183], v[36:39]
	v_mfma_f32_16x16x32_bf16 v[32:35], v[152:155], v[180:183], v[32:35]
	v_mfma_f32_16x16x32_bf16 v[20:23], v[144:147], v[188:191], v[20:23]
	v_mfma_f32_16x16x32_bf16 v[16:19], v[152:155], v[188:191], v[16:19]
	v_mfma_f32_16x16x32_bf16 v[68:71], v[148:151], v[164:167], v[68:71]
	v_mfma_f32_16x16x32_bf16 v[64:67], v[156:159], v[164:167], v[64:67]
	v_mfma_f32_16x16x32_bf16 v[52:55], v[148:151], v[172:175], v[52:55]
	v_mfma_f32_16x16x32_bf16 v[48:51], v[156:159], v[172:175], v[48:51]
	v_mfma_f32_16x16x32_bf16 v[36:39], v[148:151], v[184:187], v[36:39]
	v_mfma_f32_16x16x32_bf16 v[32:35], v[156:159], v[184:187], v[32:35]
	v_mfma_f32_16x16x32_bf16 v[20:23], v[148:151], v[192:195], v[20:23]
	v_mfma_f32_16x16x32_bf16 v[16:19], v[156:159], v[192:195], v[16:19]
	s_barrier
	s_add_i32 m0, s21, 0x14000
	s_add_u32 s64, s68, 0x40000
	s_addc_u32 s65, s69, 0
	global_load_lds_dwordx4 v0, s[64:65]
	s_add_i32 m0, s21, 0x16000
	s_add_u32 s98, s70, 0x40000
	s_addc_u32 s99, s71, 0
	global_load_lds_dwordx4 v2, s[64:65]
	s_waitcnt vmcnt(6)
	s_barrier
; #define G_STAGE(bufoff, gbase) do { _Pragma("unroll") for (int _i = 0; _i < 2; ++_i) \
;         __builtin_amdgcn_global_load_lds((const unsigned*)((const char*)(gbase) + voff[_i]), (LAS unsigned*)(lds + (bufoff) + ldsw + _i * 8192), 16, 0, 0); } while (0)
; #define G_LDA(dst, b, h) do { _Pragma("unroll") for (int m = 0; m < 4; ++m) _Pragma("unroll") for (int k = 0; k < 2; ++k) dst[m][k] = *(const LAS bf16x8*)(lds + G_SA(b, h) + aoff + m * 2048 + k * 1024); } while (0)
; #define G_LDB(dst, b, h) do { _Pragma("unroll") for (int n = 0; n < 2; ++n) _Pragma("unroll") for (int k = 0; k < 2; ++k) dst[n][k] = *(const LAS bf16x8*)(lds + G_SB(b, h) + boff + n * 2048 + k * 1024); } while (0)
; #define G_MMA(ai, bj, At, Bt) do { __builtin_amdgcn_s_setprio(1); _Pragma("unroll") for (int m = 0; m < 4; ++m) _Pragma("unroll") for (int n = 0; n < 2; ++n) _Pragma("unroll") for (int k = 0; k < 2; ++k) \
;         acc[ai][bj][m][n] = MFMA16(Bt[n][k], At[m][k], acc[ai][bj][m][n]); __builtin_amdgcn_s_setprio(0); } while (0)
; #define G_WAIT_V(n) asm volatile("s_waitcnt vmcnt(" #n ")" ::: "memory")
; #define G_WAIT_L(n) asm volatile("s_waitcnt lgkmcnt(" #n ")" ::: "memory")
; #define G_BAR __builtin_amdgcn_s_barrier()
; #define G_SCHED __builtin_amdgcn_sched_barrier(0)
; template <class Epi>
; __device__ __forceinline__ void gemm_phase(LAS unsigned char* lds, const bf16_t* Ag, const bf16_t* Btg, const int K, const int nM, const int nN, const Epi& E) {
;     ...
;             const char* a1 = cA + (size_t)(t + 1) * kstep;
;             const char* a2 = last ? nA : cA + (size_t)(t + 2) * kstep; const char* b2 = last ? nB : cB + (size_t)(t + 2) * kstep;
;             const char* a3 = a2 + kstep; const char* b3 = b2 + kstep;
;     ...
;             G_WAIT_V(6); G_BAR; G_MMA(1, 1, At, B1); G_BAR;
;             G_LDB(B0, 1, 0); G_SCHED; G_LDA(At, 1, 0); G_STAGE(G_SA(0, 1), a2 + hstep);
;             G_WAIT_L(8); G_BAR; G_WAIT_L(0); G_MMA(0, 0, At, B0); G_BAR; G_SCHED;
;             G_LDB(B1, 1, 1); G_STAGE(G_SB(1, 0), b3);
;             G_BAR; G_WAIT_L(0); G_MMA(0, 1, At, B1); G_BAR;
;             G_LDA(At, 1, 1); G_STAGE(G_SA(1, 0), a3);
;             G_BAR; G_WAIT_L(0); G_MMA(1, 0, At, B0); G_BAR; G_SCHED;
;             G_STAGE(G_SB(1, 1), b3 + hstep);
;             G_WAIT_V(6); G_BAR; G_MMA(1, 1, At, B1); G_BAR;
	v_mfma_f32_16x16x32_bf16 v[60:63], v[232:235], v[160:163], v[60:63]
	v_mfma_f32_16x16x32_bf16 v[56:59], v[240:243], v[160:163], v[56:59]
	v_mfma_f32_16x16x32_bf16 v[44:47], v[232:235], v[168:171], v[44:47]
	v_mfma_f32_16x16x32_bf16 v[40:43], v[240:243], v[168:171], v[40:43]
	v_mfma_f32_16x16x32_bf16 v[28:31], v[232:235], v[180:183], v[28:31]
	v_mfma_f32_16x16x32_bf16 v[24:27], v[240:243], v[180:183], v[24:27]
	v_mfma_f32_16x16x32_bf16 v[12:15], v[232:235], v[188:191], v[12:15]
	v_mfma_f32_16x16x32_bf16 v[8:11], v[240:243], v[188:191], v[8:11]
	v_mfma_f32_16x16x32_bf16 v[60:63], v[236:239], v[164:167], v[60:63]
	v_mfma_f32_16x16x32_bf16 v[56:59], v[244:247], v[164:167], v[56:59]
	v_mfma_f32_16x16x32_bf16 v[44:47], v[236:239], v[172:175], v[44:47]
	v_mfma_f32_16x16x32_bf16 v[40:43], v[244:247], v[172:175], v[40:43]
	v_mfma_f32_16x16x32_bf16 v[28:31], v[236:239], v[184:187], v[28:31]
	v_mfma_f32_16x16x32_bf16 v[24:27], v[244:247], v[184:187], v[24:27]
	v_mfma_f32_16x16x32_bf16 v[12:15], v[236:239], v[192:195], v[12:15]
	v_mfma_f32_16x16x32_bf16 v[8:11], v[244:247], v[192:195], v[8:11]
	s_barrier
	ds_read_b128 v[144:147], v217 offset:32768
	ds_read_b128 v[148:151], v217 offset:33792
	ds_read_b128 v[152:155], v217 offset:34816
	ds_read_b128 v[156:159], v217 offset:35840
	s_mov_b32 m0, s74
	ds_read_b128 v[160:163], v230 offset:32768
	ds_read_b128 v[164:167], v230 offset:33792
	ds_read_b128 v[168:171], v230 offset:34816
	ds_read_b128 v[172:175], v230 offset:35840
	ds_read_b128 v[180:183], v230 offset:36864
	ds_read_b128 v[184:187], v230 offset:37888
	ds_read_b128 v[188:191], v230 offset:38912
	global_load_lds_dwordx4 v0, s[98:99]
	s_mov_b32 m0, s75
	ds_read_b128 v[192:195], v230 offset:39936
	global_load_lds_dwordx4 v2, s[98:99]
	s_waitcnt lgkmcnt(8)
	s_barrier
	s_waitcnt lgkmcnt(0)
	v_mfma_f32_16x16x32_bf16 v[132:135], v[144:147], v[160:163], v[132:135]
	v_mfma_f32_16x16x32_bf16 v[128:131], v[152:155], v[160:163], v[128:131]
	v_mfma_f32_16x16x32_bf16 v[116:119], v[144:147], v[168:171], v[116:119]
	v_mfma_f32_16x16x32_bf16 v[112:115], v[152:155], v[168:171], v[112:115]
	v_mfma_f32_16x16x32_bf16 v[100:103], v[144:147], v[180:183], v[100:103]
	v_mfma_f32_16x16x32_bf16 v[96:99], v[152:155], v[180:183], v[96:99]
	v_mfma_f32_16x16x32_bf16 v[84:87], v[144:147], v[188:191], v[84:87]
	v_mfma_f32_16x16x32_bf16 v[80:83], v[152:155], v[188:191], v[80:83]
	v_mfma_f32_16x16x32_bf16 v[132:135], v[148:151], v[164:167], v[132:135]
	v_mfma_f32_16x16x32_bf16 v[128:131], v[156:159], v[164:167], v[128:131]
	v_mfma_f32_16x16x32_bf16 v[116:119], v[148:151], v[172:175], v[116:119]
	v_mfma_f32_16x16x32_bf16 v[112:115], v[156:159], v[172:175], v[112:115]
	v_mfma_f32_16x16x32_bf16 v[100:103], v[148:151], v[184:187], v[100:103]
	v_mfma_f32_16x16x32_bf16 v[96:99], v[156:159], v[184:187], v[96:99]
	v_mfma_f32_16x16x32_bf16 v[84:87], v[148:151], v[192:195], v[84:87]
	v_mfma_f32_16x16x32_bf16 v[80:83], v[156:159], v[192:195], v[80:83]
	s_barrier
	s_add_i32 m0, s21, 0x18000
	ds_read_b128 v[232:235], v217 offset:49152
	ds_read_b128 v[236:239], v217 offset:50176
	ds_read_b128 v[240:243], v217 offset:51200
	s_add_u32 s98, s68, 0x80
	s_addc_u32 s99, s69, 0
	global_load_lds_dwordx4 v0, s[98:99]
	s_add_i32 m0, s21, 0x1a000
	ds_read_b128 v[244:247], v217 offset:52224
	global_load_lds_dwordx4 v2, s[98:99]
	s_barrier
	s_waitcnt lgkmcnt(0)
	v_mfma_f32_16x16x32_bf16 v[124:127], v[232:235], v[160:163], v[124:127]
	v_mfma_f32_16x16x32_bf16 v[120:123], v[240:243], v[160:163], v[120:123]
	v_mfma_f32_16x16x32_bf16 v[108:111], v[232:235], v[168:171], v[108:111]
	v_mfma_f32_16x16x32_bf16 v[104:107], v[240:243], v[168:171], v[104:107]
	v_mfma_f32_16x16x32_bf16 v[92:95], v[232:235], v[180:183], v[92:95]
	v_mfma_f32_16x16x32_bf16 v[88:91], v[240:243], v[180:183], v[88:91]
	v_mfma_f32_16x16x32_bf16 v[76:79], v[232:235], v[188:191], v[76:79]
	v_mfma_f32_16x16x32_bf16 v[72:75], v[240:243], v[188:191], v[72:75]
	v_mfma_f32_16x16x32_bf16 v[124:127], v[236:239], v[164:167], v[124:127]
	v_mfma_f32_16x16x32_bf16 v[120:123], v[244:247], v[164:167], v[120:123]
	v_mfma_f32_16x16x32_bf16 v[108:111], v[236:239], v[172:175], v[108:111]
	v_mfma_f32_16x16x32_bf16 v[104:107], v[244:247], v[172:175], v[104:107]
	v_mfma_f32_16x16x32_bf16 v[92:95], v[236:239], v[184:187], v[92:95]
	v_mfma_f32_16x16x32_bf16 v[88:91], v[244:247], v[184:187], v[88:91]
	v_mfma_f32_16x16x32_bf16 v[76:79], v[236:239], v[192:195], v[76:79]
	v_mfma_f32_16x16x32_bf16 v[72:75], v[244:247], v[192:195], v[72:75]
	s_mov_b32 m0, s76
	s_barrier
	ds_read_b128 v[160:163], v230 offset:49152
	ds_read_b128 v[164:167], v230 offset:50176
	ds_read_b128 v[168:171], v230 offset:51200
	ds_read_b128 v[172:175], v230 offset:52224
	ds_read_b128 v[180:183], v230 offset:53248
	ds_read_b128 v[184:187], v230 offset:54272
	ds_read_b128 v[188:191], v230 offset:55296
	s_add_u32 s98, s70, 0x80
	s_addc_u32 s99, s71, 0
	global_load_lds_dwordx4 v0, s[98:99]
	s_mov_b32 m0, s77
	ds_read_b128 v[192:195], v230 offset:56320
	global_load_lds_dwordx4 v2, s[98:99]
	s_barrier
	s_waitcnt lgkmcnt(0)
	v_mfma_f32_16x16x32_bf16 v[68:71], v[144:147], v[160:163], v[68:71]
	v_mfma_f32_16x16x32_bf16 v[64:67], v[152:155], v[160:163], v[64:67]
	v_mfma_f32_16x16x32_bf16 v[52:55], v[144:147], v[168:171], v[52:55]
	v_mfma_f32_16x16x32_bf16 v[48:51], v[152:155], v[168:171], v[48:51]
	v_mfma_f32_16x16x32_bf16 v[36:39], v[144:147], v[180:183], v[36:39]
	v_mfma_f32_16x16x32_bf16 v[32:35], v[152:155], v[180:183], v[32:35]
	v_mfma_f32_16x16x32_bf16 v[20:23], v[144:147], v[188:191], v[20:23]
	v_mfma_f32_16x16x32_bf16 v[16:19], v[152:155], v[188:191], v[16:19]
	v_mfma_f32_16x16x32_bf16 v[68:71], v[148:151], v[164:167], v[68:71]
	v_mfma_f32_16x16x32_bf16 v[64:67], v[156:159], v[164:167], v[64:67]
	v_mfma_f32_16x16x32_bf16 v[52:55], v[148:151], v[172:175], v[52:55]
	v_mfma_f32_16x16x32_bf16 v[48:51], v[156:159], v[172:175], v[48:51]
	v_mfma_f32_16x16x32_bf16 v[36:39], v[148:151], v[184:187], v[36:39]
	v_mfma_f32_16x16x32_bf16 v[32:35], v[156:159], v[184:187], v[32:35]
	v_mfma_f32_16x16x32_bf16 v[20:23], v[148:151], v[192:195], v[20:23]
	v_mfma_f32_16x16x32_bf16 v[16:19], v[156:159], v[192:195], v[16:19]
	s_barrier
	s_add_i32 m0, s21, 0x1c000
	s_add_u32 s64, s68, 0x40080
	s_addc_u32 s65, s69, 0
	global_load_lds_dwordx4 v0, s[64:65]
	s_add_i32 m0, s21, 0x1e000
	s_add_i32 s42, s42, 2
	global_load_lds_dwordx4 v2, s[64:65]
	s_add_u32 s57, s57, 0x100
	s_addc_u32 s61, s61, 0
	s_mov_b64 s[64:65], s[66:67]
	s_cmp_gt_u32 s42, 13
	s_cbranch_scc1 .LrotX_153
	s_cmp_lg_u32 s42, 12
	s_cselect_b64 s[68:69], -1, 0
	s_add_u32 s66, s64, 0x100
	s_addc_u32 s67, s65, 0
	s_and_b64 s[68:69], s[68:69], exec
	s_cselect_b32 s71, s67, s55
	s_cselect_b32 s70, s66, s54
	s_cselect_b32 s69, s61, s14
	s_cselect_b32 s68, s57, s15

; #define G_STAGE(bufoff, gbase) do { _Pragma("unroll") for (int _i = 0; _i < 2; ++_i) \
;         __builtin_amdgcn_global_load_lds((const unsigned*)((const char*)(gbase) + voff[_i]), (LAS unsigned*)(lds + (bufoff) + ldsw + _i * 8192), 16, 0, 0); } while (0)
; #define G_LDA(dst, b, h) do { _Pragma("unroll") for (int m = 0; m < 4; ++m) _Pragma("unroll") for (int k = 0; k < 2; ++k) dst[m][k] = *(const LAS bf16x8*)(lds + G_SA(b, h) + aoff + m * 2048 + k * 1024); } while (0)
; #define G_LDB(dst, b, h) do { _Pragma("unroll") for (int n = 0; n < 2; ++n) _Pragma("unroll") for (int k = 0; k < 2; ++k) dst[n][k] = *(const LAS bf16x8*)(lds + G_SB(b, h) + boff + n * 2048 + k * 1024); } while (0)
; #define G_MMA(ai, bj, At, Bt) do { __builtin_amdgcn_s_setprio(1); _Pragma("unroll") for (int m = 0; m < 4; ++m) _Pragma("unroll") for (int n = 0; n < 2; ++n) _Pragma("unroll") for (int k = 0; k < 2; ++k) \
;         acc[ai][bj][m][n] = MFMA16(Bt[n][k], At[m][k], acc[ai][bj][m][n]); __builtin_amdgcn_s_setprio(0); } while (0)
; #define G_WAIT_V(n) asm volatile("s_waitcnt vmcnt(" #n ")" ::: "memory")
; #define G_WAIT_L(n) asm volatile("s_waitcnt lgkmcnt(" #n ")" ::: "memory")
; #define G_BAR __builtin_amdgcn_s_barrier()
; #define G_SCHED __builtin_amdgcn_sched_barrier(0)
; template <class Epi>
; __device__ __forceinline__ void gemm_phase(LAS unsigned char* lds, const bf16_t* Ag, const bf16_t* Btg, const int K, const int nM, const int nN, const Epi& E) {
;     ...
;             G_LDB(B0, 0, 0); G_SCHED; G_LDA(At, 0, 0); G_STAGE(G_SA(1, 1), a1 + hstep);
;             G_WAIT_L(8); G_BAR; G_WAIT_L(0); G_MMA(0, 0, At, B0); G_BAR; G_SCHED;
;             G_LDB(B1, 0, 1); G_STAGE(G_SB(0, 0), b2);
;             G_BAR; G_WAIT_L(0); G_MMA(0, 1, At, B1); G_BAR;
;             G_LDA(At, 0, 1); G_STAGE(G_SA(0, 0), a2);
;             G_BAR; G_WAIT_L(0); G_MMA(1, 0, At, B0); G_BAR; G_SCHED;
;             G_STAGE(G_SB(0, 1), b2 + hstep);
;             G_WAIT_V(6); G_BAR; G_MMA(1, 1, At, B1); G_BAR;
.LmainW_744:
	ds_read_b128 v[140:143], v217
	ds_read_b128 v[144:147], v217 offset:1024
	ds_read_b128 v[148:151], v217 offset:2048
	ds_read_b128 v[152:155], v217 offset:3072
	s_add_i32 m0, s66, 0xc000
	ds_read_b128 v[156:159], v174
	ds_read_b128 v[160:163], v174 offset:1024
	ds_read_b128 v[180:183], v174 offset:2048
	ds_read_b128 v[184:187], v174 offset:3072
	ds_read_b128 v[188:191], v174 offset:4096
	ds_read_b128 v[192:195], v174 offset:5120
	ds_read_b128 v[222:225], v174 offset:6144
	global_load_lds_dwordx4 v138, s[56:57]
	s_add_i32 m0, s66, 0xe000
	ds_read_b128 v[226:229], v174 offset:7168
	global_load_lds_dwordx4 v136, s[56:57]
	s_waitcnt lgkmcnt(8)
	s_barrier
	s_waitcnt lgkmcnt(0)
	v_mfma_f32_16x16x32_bf16 v[132:135], v[140:143], v[156:159], v[132:135]
	v_mfma_f32_16x16x32_bf16 v[128:131], v[148:151], v[156:159], v[128:131]
	v_mfma_f32_16x16x32_bf16 v[116:119], v[140:143], v[180:183], v[116:119]
	v_mfma_f32_16x16x32_bf16 v[112:115], v[148:151], v[180:183], v[112:115]
	v_mfma_f32_16x16x32_bf16 v[100:103], v[140:143], v[188:191], v[100:103]
	v_mfma_f32_16x16x32_bf16 v[96:99], v[148:151], v[188:191], v[96:99]
	v_mfma_f32_16x16x32_bf16 v[84:87], v[140:143], v[222:225], v[84:87]
	v_mfma_f32_16x16x32_bf16 v[80:83], v[148:151], v[222:225], v[80:83]
	v_mfma_f32_16x16x32_bf16 v[132:135], v[144:147], v[160:163], v[132:135]
	v_mfma_f32_16x16x32_bf16 v[128:131], v[152:155], v[160:163], v[128:131]
	v_mfma_f32_16x16x32_bf16 v[116:119], v[144:147], v[184:187], v[116:119]
	v_mfma_f32_16x16x32_bf16 v[112:115], v[152:155], v[184:187], v[112:115]
	v_mfma_f32_16x16x32_bf16 v[100:103], v[144:147], v[192:195], v[100:103]
	v_mfma_f32_16x16x32_bf16 v[96:99], v[152:155], v[192:195], v[96:99]
	v_mfma_f32_16x16x32_bf16 v[84:87], v[144:147], v[226:229], v[84:87]
	v_mfma_f32_16x16x32_bf16 v[80:83], v[152:155], v[226:229], v[80:83]
	s_barrier
	s_add_i32 m0, s65, 0x10000
	ds_read_b128 v[230:233], v217 offset:16384
	ds_read_b128 v[234:237], v217 offset:17408
	ds_read_b128 v[238:241], v217 offset:18432
	global_load_lds_dwordx4 v0, s[60:61]
	s_add_i32 m0, s65, 0x12000
	ds_read_b128 v[242:245], v217 offset:19456
	global_load_lds_dwordx4 v2, s[60:61]
	s_barrier
	s_waitcnt lgkmcnt(0)
	v_mfma_f32_16x16x32_bf16 v[124:127], v[230:233], v[156:159], v[124:127]
	v_mfma_f32_16x16x32_bf16 v[120:123], v[238:241], v[156:159], v[120:123]
	v_mfma_f32_16x16x32_bf16 v[108:111], v[230:233], v[180:183], v[108:111]
	v_mfma_f32_16x16x32_bf16 v[104:107], v[238:241], v[180:183], v[104:107]
	v_mfma_f32_16x16x32_bf16 v[92:95], v[230:233], v[188:191], v[92:95]
	v_mfma_f32_16x16x32_bf16 v[88:91], v[238:241], v[188:191], v[88:91]
	v_mfma_f32_16x16x32_bf16 v[76:79], v[230:233], v[222:225], v[76:79]
	v_mfma_f32_16x16x32_bf16 v[72:75], v[238:241], v[222:225], v[72:75]
	v_mfma_f32_16x16x32_bf16 v[124:127], v[234:237], v[160:163], v[124:127]
	v_mfma_f32_16x16x32_bf16 v[120:123], v[242:245], v[160:163], v[120:123]
	v_mfma_f32_16x16x32_bf16 v[108:111], v[234:237], v[184:187], v[108:111]
	v_mfma_f32_16x16x32_bf16 v[104:107], v[242:245], v[184:187], v[104:107]
	v_mfma_f32_16x16x32_bf16 v[92:95], v[234:237], v[192:195], v[92:95]
	v_mfma_f32_16x16x32_bf16 v[88:91], v[242:245], v[192:195], v[88:91]
	v_mfma_f32_16x16x32_bf16 v[76:79], v[234:237], v[226:229], v[76:79]
	v_mfma_f32_16x16x32_bf16 v[72:75], v[242:245], v[226:229], v[72:75]
	s_mov_b32 m0, s66
	s_barrier
	ds_read_b128 v[156:159], v174 offset:16384
	ds_read_b128 v[160:163], v174 offset:17408
	ds_read_b128 v[180:183], v174 offset:18432
	ds_read_b128 v[184:187], v174 offset:19456
	ds_read_b128 v[188:191], v174 offset:20480
	ds_read_b128 v[192:195], v174 offset:21504
	ds_read_b128 v[222:225], v174 offset:22528
	global_load_lds_dwordx4 v0, s[62:63]
	s_mov_b32 m0, s67
	ds_read_b128 v[226:229], v174 offset:23552
	global_load_lds_dwordx4 v2, s[62:63]
	s_barrier
	s_waitcnt lgkmcnt(0)
	v_mfma_f32_16x16x32_bf16 v[68:71], v[140:143], v[156:159], v[68:71]
	v_mfma_f32_16x16x32_bf16 v[64:67], v[148:151], v[156:159], v[64:67]
	v_mfma_f32_16x16x32_bf16 v[52:55], v[140:143], v[180:183], v[52:55]
	v_mfma_f32_16x16x32_bf16 v[48:51], v[148:151], v[180:183], v[48:51]
	v_mfma_f32_16x16x32_bf16 v[36:39], v[140:143], v[188:191], v[36:39]
	v_mfma_f32_16x16x32_bf16 v[32:35], v[148:151], v[188:191], v[32:35]
	v_mfma_f32_16x16x32_bf16 v[20:23], v[140:143], v[222:225], v[20:23]
	v_mfma_f32_16x16x32_bf16 v[16:19], v[148:151], v[222:225], v[16:19]
	v_mfma_f32_16x16x32_bf16 v[68:71], v[144:147], v[160:163], v[68:71]
	v_mfma_f32_16x16x32_bf16 v[64:67], v[152:155], v[160:163], v[64:67]
	v_mfma_f32_16x16x32_bf16 v[52:55], v[144:147], v[184:187], v[52:55]
	v_mfma_f32_16x16x32_bf16 v[48:51], v[152:155], v[184:187], v[48:51]
	v_mfma_f32_16x16x32_bf16 v[36:39], v[144:147], v[192:195], v[36:39]
	v_mfma_f32_16x16x32_bf16 v[32:35], v[152:155], v[192:195], v[32:35]
	v_mfma_f32_16x16x32_bf16 v[20:23], v[144:147], v[226:229], v[20:23]
	v_mfma_f32_16x16x32_bf16 v[16:19], v[152:155], v[226:229], v[16:19]
	s_barrier
	s_add_i32 m0, s65, 0x14000
	s_add_u32 s56, s60, 0x100000
	s_addc_u32 s57, s61, 0
	global_load_lds_dwordx4 v0, s[56:57]
	s_add_i32 m0, s65, 0x16000
	s_add_u32 s98, s62, 0x100000
	s_addc_u32 s99, s63, 0
	global_load_lds_dwordx4 v2, s[56:57]
	s_waitcnt vmcnt(6)
	s_barrier
;     __device__ __forceinline__ void prep(int pm, int par, LAS unsigned char* lds) const { if (fold) prep_rowstats(stat, pm, par, lds); }
;     __device__ __forceinline__ void prep(int pm, int par, LAS unsigned char* lds) const { if (!ident) prep_rowstats(stat, pm, par, lds); }
;     __device__ __forceinline__ void prep(int pm, int par, LAS unsigned char* lds) const { prep_rowstats(stat, pm, par, lds); }
; #define G_STAGE(bufoff, gbase) do { _Pragma("unroll") for (int _i = 0; _i < 2; ++_i) \
;         __builtin_amdgcn_global_load_lds((const unsigned*)((const char*)(gbase) + voff[_i]), (LAS unsigned*)(lds + (bufoff) + ldsw + _i * 8192), 16, 0, 0); } while (0)
; #define G_WAIT_V(n) asm volatile("s_waitcnt vmcnt(" #n ")" ::: "memory")
; #define G_BAR __builtin_amdgcn_s_barrier()
; template <class Epi>
; __device__ __forceinline__ void gemm_phase(LAS unsigned char* lds, const bf16_t* Ag, const bf16_t* Btg, const int K, const int nM, const int nN, const Epi& E) {
;     ...
;         for (int t = 0; t < nt; t += 2) {
;             const bool last = (t == nt - 2);
;             const char* a1 = cA + (size_t)(t + 1) * kstep;
;             const char* a2 = last ? nA : cA + (size_t)(t + 2) * kstep; const char* b2 = last ? nB : cB + (size_t)(t + 2) * kstep;
;             const char* a3 = a2 + kstep; const char* b3 = b2 + kstep;
;             if (last && has_next && pmn != pm) E.prep(pmn, par ^ 1, lds);
;             G_LDB(B0, 0, 0); G_SCHED; G_LDA(At, 0, 0); G_STAGE(G_SA(1, 1), a1 + hstep);
;             G_WAIT_L(8); G_BAR; G_WAIT_L(0); G_MMA(0, 0, At, B0); G_BAR; G_SCHED;
;             G_LDB(B1, 0, 1); G_STAGE(G_SB(0, 0), b2);
;             G_BAR; G_WAIT_L(0); G_MMA(0, 1, At, B1); G_BAR;
;             G_LDA(At, 0, 1); G_STAGE(G_SA(0, 0), a2);
;             G_BAR; G_WAIT_L(0); G_MMA(1, 0, At, B0); G_BAR; G_SCHED;
;             G_STAGE(G_SB(0, 1), b2 + hstep);
;             G_WAIT_V(6); G_BAR; G_MMA(1, 1, At, B1); G_BAR;
;             G_LDB(B0, 1, 0); G_SCHED; G_LDA(At, 1, 0); G_STAGE(G_SA(0, 1), a2 + hstep);
;             G_WAIT_L(8); G_BAR; G_WAIT_L(0); G_MMA(0, 0, At, B0); G_BAR; G_SCHED;
;             G_LDB(B1, 1, 1); G_STAGE(G_SB(1, 0), b3);
;             G_BAR; G_WAIT_L(0); G_MMA(0, 1, At, B1); G_BAR;
;             G_LDA(At, 1, 1); G_STAGE(G_SA(1, 0), a3);
;             G_BAR; G_WAIT_L(0); G_MMA(1, 0, At, B0); G_BAR; G_SCHED;
;             G_STAGE(G_SB(1, 1), b3 + hstep);
	v_mfma_f32_16x16x32_bf16 v[60:63], v[230:233], v[156:159], v[60:63]
	v_mfma_f32_16x16x32_bf16 v[56:59], v[238:241], v[156:159], v[56:59]
	v_mfma_f32_16x16x32_bf16 v[44:47], v[230:233], v[180:183], v[44:47]
	v_mfma_f32_16x16x32_bf16 v[40:43], v[238:241], v[180:183], v[40:43]
	v_mfma_f32_16x16x32_bf16 v[28:31], v[230:233], v[188:191], v[28:31]
	v_mfma_f32_16x16x32_bf16 v[24:27], v[238:241], v[188:191], v[24:27]
	v_mfma_f32_16x16x32_bf16 v[12:15], v[230:233], v[222:225], v[12:15]
	v_mfma_f32_16x16x32_bf16 v[8:11], v[238:241], v[222:225], v[8:11]
	v_mfma_f32_16x16x32_bf16 v[60:63], v[234:237], v[160:163], v[60:63]
	v_mfma_f32_16x16x32_bf16 v[56:59], v[242:245], v[160:163], v[56:59]
	v_mfma_f32_16x16x32_bf16 v[44:47], v[234:237], v[184:187], v[44:47]
	v_mfma_f32_16x16x32_bf16 v[40:43], v[242:245], v[184:187], v[40:43]
	v_mfma_f32_16x16x32_bf16 v[28:31], v[234:237], v[192:195], v[28:31]
	v_mfma_f32_16x16x32_bf16 v[24:27], v[242:245], v[192:195], v[24:27]
	v_mfma_f32_16x16x32_bf16 v[12:15], v[234:237], v[226:229], v[12:15]
	v_mfma_f32_16x16x32_bf16 v[8:11], v[242:245], v[226:229], v[8:11]
	s_barrier
	ds_read_b128 v[140:143], v217 offset:32768
	ds_read_b128 v[144:147], v217 offset:33792
	ds_read_b128 v[148:151], v217 offset:34816
	ds_read_b128 v[152:155], v217 offset:35840
	s_mov_b32 m0, s68
	ds_read_b128 v[156:159], v174 offset:32768
	ds_read_b128 v[160:163], v174 offset:33792
	ds_read_b128 v[180:183], v174 offset:34816
	ds_read_b128 v[184:187], v174 offset:35840
	ds_read_b128 v[188:191], v174 offset:36864
	ds_read_b128 v[192:195], v174 offset:37888
	ds_read_b128 v[222:225], v174 offset:38912
	global_load_lds_dwordx4 v0, s[98:99]
	s_mov_b32 m0, s69
	ds_read_b128 v[226:229], v174 offset:39936
	global_load_lds_dwordx4 v2, s[98:99]
	s_waitcnt lgkmcnt(8)
	s_barrier
	s_waitcnt lgkmcnt(0)
	v_mfma_f32_16x16x32_bf16 v[132:135], v[140:143], v[156:159], v[132:135]
	v_mfma_f32_16x16x32_bf16 v[128:131], v[148:151], v[156:159], v[128:131]
	v_mfma_f32_16x16x32_bf16 v[116:119], v[140:143], v[180:183], v[116:119]
	v_mfma_f32_16x16x32_bf16 v[112:115], v[148:151], v[180:183], v[112:115]
	v_mfma_f32_16x16x32_bf16 v[100:103], v[140:143], v[188:191], v[100:103]
	v_mfma_f32_16x16x32_bf16 v[96:99], v[148:151], v[188:191], v[96:99]
	v_mfma_f32_16x16x32_bf16 v[84:87], v[140:143], v[222:225], v[84:87]
	v_mfma_f32_16x16x32_bf16 v[80:83], v[148:151], v[222:225], v[80:83]
	v_mfma_f32_16x16x32_bf16 v[132:135], v[144:147], v[160:163], v[132:135]
	v_mfma_f32_16x16x32_bf16 v[128:131], v[152:155], v[160:163], v[128:131]
	v_mfma_f32_16x16x32_bf16 v[116:119], v[144:147], v[184:187], v[116:119]
	v_mfma_f32_16x16x32_bf16 v[112:115], v[152:155], v[184:187], v[112:115]
	v_mfma_f32_16x16x32_bf16 v[100:103], v[144:147], v[192:195], v[100:103]
	v_mfma_f32_16x16x32_bf16 v[96:99], v[152:155], v[192:195], v[96:99]
	v_mfma_f32_16x16x32_bf16 v[84:87], v[144:147], v[226:229], v[84:87]
	v_mfma_f32_16x16x32_bf16 v[80:83], v[152:155], v[226:229], v[80:83]
	s_barrier
	s_add_i32 m0, s65, 0x18000
	ds_read_b128 v[230:233], v217 offset:49152
	ds_read_b128 v[234:237], v217 offset:50176
	ds_read_b128 v[238:241], v217 offset:51200
	s_add_u32 s98, s60, 0x80
	s_addc_u32 s99, s61, 0
	global_load_lds_dwordx4 v0, s[98:99]
	s_add_i32 m0, s65, 0x1a000
	ds_read_b128 v[242:245], v217 offset:52224
	global_load_lds_dwordx4 v2, s[98:99]
	s_barrier
	s_waitcnt lgkmcnt(0)
	v_mfma_f32_16x16x32_bf16 v[124:127], v[230:233], v[156:159], v[124:127]
	v_mfma_f32_16x16x32_bf16 v[120:123], v[238:241], v[156:159], v[120:123]
	v_mfma_f32_16x16x32_bf16 v[108:111], v[230:233], v[180:183], v[108:111]
	v_mfma_f32_16x16x32_bf16 v[104:107], v[238:241], v[180:183], v[104:107]
	v_mfma_f32_16x16x32_bf16 v[92:95], v[230:233], v[188:191], v[92:95]
	v_mfma_f32_16x16x32_bf16 v[88:91], v[238:241], v[188:191], v[88:91]
	v_mfma_f32_16x16x32_bf16 v[76:79], v[230:233], v[222:225], v[76:79]
	v_mfma_f32_16x16x32_bf16 v[72:75], v[238:241], v[222:225], v[72:75]
	v_mfma_f32_16x16x32_bf16 v[124:127], v[234:237], v[160:163], v[124:127]
	v_mfma_f32_16x16x32_bf16 v[120:123], v[242:245], v[160:163], v[120:123]
	v_mfma_f32_16x16x32_bf16 v[108:111], v[234:237], v[184:187], v[108:111]
	v_mfma_f32_16x16x32_bf16 v[104:107], v[242:245], v[184:187], v[104:107]
	v_mfma_f32_16x16x32_bf16 v[92:95], v[234:237], v[192:195], v[92:95]
	v_mfma_f32_16x16x32_bf16 v[88:91], v[242:245], v[192:195], v[88:91]
	v_mfma_f32_16x16x32_bf16 v[76:79], v[234:237], v[226:229], v[76:79]
	v_mfma_f32_16x16x32_bf16 v[72:75], v[242:245], v[226:229], v[72:75]
	s_mov_b32 m0, s70
	s_barrier
	ds_read_b128 v[156:159], v174 offset:49152
	ds_read_b128 v[160:163], v174 offset:50176
	ds_read_b128 v[180:183], v174 offset:51200
	ds_read_b128 v[184:187], v174 offset:52224
	ds_read_b128 v[188:191], v174 offset:53248
	ds_read_b128 v[192:195], v174 offset:54272
	ds_read_b128 v[222:225], v174 offset:55296
	s_add_u32 s98, s62, 0x80
	s_addc_u32 s99, s63, 0
	global_load_lds_dwordx4 v0, s[98:99]
	s_mov_b32 m0, s71
	ds_read_b128 v[226:229], v174 offset:56320
	global_load_lds_dwordx4 v2, s[98:99]
	s_barrier
	s_waitcnt lgkmcnt(0)
	v_mfma_f32_16x16x32_bf16 v[68:71], v[140:143], v[156:159], v[68:71]
	v_mfma_f32_16x16x32_bf16 v[64:67], v[148:151], v[156:159], v[64:67]
	v_mfma_f32_16x16x32_bf16 v[52:55], v[140:143], v[180:183], v[52:55]
	v_mfma_f32_16x16x32_bf16 v[48:51], v[148:151], v[180:183], v[48:51]
	v_mfma_f32_16x16x32_bf16 v[36:39], v[140:143], v[188:191], v[36:39]
	v_mfma_f32_16x16x32_bf16 v[32:35], v[148:151], v[188:191], v[32:35]
	v_mfma_f32_16x16x32_bf16 v[20:23], v[140:143], v[222:225], v[20:23]
	v_mfma_f32_16x16x32_bf16 v[16:19], v[148:151], v[222:225], v[16:19]
	v_mfma_f32_16x16x32_bf16 v[68:71], v[144:147], v[160:163], v[68:71]
	v_mfma_f32_16x16x32_bf16 v[64:67], v[152:155], v[160:163], v[64:67]
	v_mfma_f32_16x16x32_bf16 v[52:55], v[144:147], v[184:187], v[52:55]
	v_mfma_f32_16x16x32_bf16 v[48:51], v[152:155], v[184:187], v[48:51]
	v_mfma_f32_16x16x32_bf16 v[36:39], v[144:147], v[192:195], v[36:39]
	v_mfma_f32_16x16x32_bf16 v[32:35], v[152:155], v[192:195], v[32:35]
	v_mfma_f32_16x16x32_bf16 v[20:23], v[144:147], v[226:229], v[20:23]
	v_mfma_f32_16x16x32_bf16 v[16:19], v[152:155], v[226:229], v[16:19]
	s_barrier
	s_add_i32 m0, s65, 0x1c000
	s_add_u32 s56, s60, 0x100080
	s_addc_u32 s57, s61, 0
	global_load_lds_dwordx4 v0, s[56:57]
	s_add_i32 m0, s65, 0x1e000
	s_add_i32 s79, s79, 2
	global_load_lds_dwordx4 v2, s[56:57]
	s_add_u32 s77, s77, 0x100
	s_addc_u32 s78, s78, 0
	s_mov_b64 s[56:57], s[58:59]
	s_cmp_gt_u32 s79, 61
	s_cbranch_scc1 .LrotX_744
	s_cmp_lg_u32 s79, 60
	s_cselect_b64 s[60:61], -1, 0
	s_add_u32 s58, s56, 0x100
	s_addc_u32 s59, s57, 0
	s_and_b64 s[60:61], s[60:61], exec
	s_cselect_b32 s63, s59, s47
	s_cselect_b32 s62, s58, s46
	s_cselect_b32 s61, s78, s15
	s_cselect_b32 s60, s77, s49

; #define G_STAGE(bufoff, gbase) do { _Pragma("unroll") for (int _i = 0; _i < 2; ++_i) \
;         __builtin_amdgcn_global_load_lds((const unsigned*)((const char*)(gbase) + voff[_i]), (LAS unsigned*)(lds + (bufoff) + ldsw + _i * 8192), 16, 0, 0); } while (0)
; #define G_LDA(dst, b, h) do { _Pragma("unroll") for (int m = 0; m < 4; ++m) _Pragma("unroll") for (int k = 0; k < 2; ++k) dst[m][k] = *(const LAS bf16x8*)(lds + G_SA(b, h) + aoff + m * 2048 + k * 1024); } while (0)
; #define G_LDB(dst, b, h) do { _Pragma("unroll") for (int n = 0; n < 2; ++n) _Pragma("unroll") for (int k = 0; k < 2; ++k) dst[n][k] = *(const LAS bf16x8*)(lds + G_SB(b, h) + boff + n * 2048 + k * 1024); } while (0)
; #define G_MMA(ai, bj, At, Bt) do { __builtin_amdgcn_s_setprio(1); _Pragma("unroll") for (int m = 0; m < 4; ++m) _Pragma("unroll") for (int n = 0; n < 2; ++n) _Pragma("unroll") for (int k = 0; k < 2; ++k) \
;         acc[ai][bj][m][n] = MFMA16(Bt[n][k], At[m][k], acc[ai][bj][m][n]); __builtin_amdgcn_s_setprio(0); } while (0)
; #define G_WAIT_V(n) asm volatile("s_waitcnt vmcnt(" #n ")" ::: "memory")
; #define G_WAIT_L(n) asm volatile("s_waitcnt lgkmcnt(" #n ")" ::: "memory")
; #define G_BAR __builtin_amdgcn_s_barrier()
; #define G_SCHED __builtin_amdgcn_sched_barrier(0)
; template <class Epi>
; __device__ __forceinline__ void gemm_phase(LAS unsigned char* lds, const bf16_t* Ag, const bf16_t* Btg, const int K, const int nM, const int nN, const Epi& E) {
;     ...
;             G_LDB(B0, 0, 0); G_SCHED; G_LDA(At, 0, 0); G_STAGE(G_SA(1, 1), a1 + hstep);
;             G_WAIT_L(8); G_BAR; G_WAIT_L(0); G_MMA(0, 0, At, B0); G_BAR; G_SCHED;
;             G_LDB(B1, 0, 1); G_STAGE(G_SB(0, 0), b2);
;             G_BAR; G_WAIT_L(0); G_MMA(0, 1, At, B1); G_BAR;
;             G_LDA(At, 0, 1); G_STAGE(G_SA(0, 0), a2);
;             G_BAR; G_WAIT_L(0); G_MMA(1, 0, At, B0); G_BAR; G_SCHED;
;             G_STAGE(G_SB(0, 1), b2 + hstep);
;             G_WAIT_V(6); G_BAR; G_MMA(1, 1, At, B1); G_BAR;
.LmainW_848:
	ds_read_b128 v[130:133], v217
	ds_read_b128 v[134:137], v217 offset:1024
	ds_read_b128 v[144:147], v217 offset:2048
	ds_read_b128 v[148:151], v217 offset:3072
	s_add_i32 m0, s60, 0xc000
	ds_read_b128 v[156:159], v222
	ds_read_b128 v[160:163], v222 offset:1024
	ds_read_b128 v[164:167], v222 offset:2048
	ds_read_b128 v[180:183], v222 offset:3072
	ds_read_b128 v[184:187], v222 offset:4096
	ds_read_b128 v[224:227], v222 offset:5120
	ds_read_b128 v[228:231], v222 offset:6144
	global_load_lds_dwordx4 v170, s[50:51]
	s_add_i32 m0, s60, 0xe000
	ds_read_b128 v[232:235], v222 offset:7168
	global_load_lds_dwordx4 v168, s[50:51]
	s_waitcnt lgkmcnt(8)
	s_barrier
	s_waitcnt lgkmcnt(0)
	v_mfma_f32_16x16x32_bf16 v[152:155], v[130:133], v[156:159], v[152:155]
	v_mfma_f32_16x16x32_bf16 v[138:141], v[144:147], v[156:159], v[140:143]
	v_mfma_f32_16x16x32_bf16 v[116:119], v[130:133], v[164:167], v[116:119]
	v_mfma_f32_16x16x32_bf16 v[112:115], v[144:147], v[164:167], v[112:115]
	v_mfma_f32_16x16x32_bf16 v[100:103], v[130:133], v[184:187], v[100:103]
	v_mfma_f32_16x16x32_bf16 v[96:99], v[144:147], v[184:187], v[96:99]
	v_mfma_f32_16x16x32_bf16 v[84:87], v[130:133], v[228:231], v[84:87]
	v_mfma_f32_16x16x32_bf16 v[80:83], v[144:147], v[228:231], v[80:83]
	v_mfma_f32_16x16x32_bf16 v[152:155], v[134:137], v[160:163], v[152:155]
	v_mfma_f32_16x16x32_bf16 v[138:141], v[148:151], v[160:163], v[138:141]
	v_mfma_f32_16x16x32_bf16 v[116:119], v[134:137], v[180:183], v[116:119]
	v_mfma_f32_16x16x32_bf16 v[112:115], v[148:151], v[180:183], v[112:115]
	v_mfma_f32_16x16x32_bf16 v[100:103], v[134:137], v[224:227], v[100:103]
	v_mfma_f32_16x16x32_bf16 v[96:99], v[148:151], v[224:227], v[96:99]
	v_mfma_f32_16x16x32_bf16 v[84:87], v[134:137], v[232:235], v[84:87]
	v_mfma_f32_16x16x32_bf16 v[80:83], v[148:151], v[232:235], v[80:83]
	s_barrier
	s_add_i32 s73, 0, 0x14000
	s_add_i32 m0, s59, 0x10000
	ds_read_b128 v[236:239], v217 offset:16384
	ds_read_b128 v[240:243], v217 offset:17408
	ds_read_b128 v[244:247], v217 offset:18432
	global_load_lds_dwordx4 v0, s[52:53]
	s_add_i32 m0, s59, 0x12000
	ds_read_b128 v[248:251], v217 offset:19456
	global_load_lds_dwordx4 v2, s[52:53]
	s_barrier
	s_waitcnt lgkmcnt(0)
	v_mfma_f32_16x16x32_bf16 v[124:127], v[236:239], v[156:159], v[124:127]
	v_mfma_f32_16x16x32_bf16 v[120:123], v[244:247], v[156:159], v[120:123]
	v_mfma_f32_16x16x32_bf16 v[108:111], v[236:239], v[164:167], v[108:111]
	v_mfma_f32_16x16x32_bf16 v[104:107], v[244:247], v[164:167], v[104:107]
	v_mfma_f32_16x16x32_bf16 v[92:95], v[236:239], v[184:187], v[92:95]
	v_mfma_f32_16x16x32_bf16 v[88:91], v[244:247], v[184:187], v[88:91]
	v_mfma_f32_16x16x32_bf16 v[76:79], v[236:239], v[228:231], v[76:79]
	v_mfma_f32_16x16x32_bf16 v[72:75], v[244:247], v[228:231], v[72:75]
	v_mfma_f32_16x16x32_bf16 v[124:127], v[240:243], v[160:163], v[124:127]
	v_mfma_f32_16x16x32_bf16 v[120:123], v[248:251], v[160:163], v[120:123]
	v_mfma_f32_16x16x32_bf16 v[108:111], v[240:243], v[180:183], v[108:111]
	v_mfma_f32_16x16x32_bf16 v[104:107], v[248:251], v[180:183], v[104:107]
	v_mfma_f32_16x16x32_bf16 v[92:95], v[240:243], v[224:227], v[92:95]
	v_mfma_f32_16x16x32_bf16 v[88:91], v[248:251], v[224:227], v[88:91]
	v_mfma_f32_16x16x32_bf16 v[76:79], v[240:243], v[232:235], v[76:79]
	v_mfma_f32_16x16x32_bf16 v[72:75], v[248:251], v[232:235], v[72:75]
	s_mov_b32 m0, s60
	s_add_u32 s76, s54, 0x80
	s_addc_u32 s77, s55, 0
	s_barrier
	ds_read_b128 v[156:159], v222 offset:16384
	ds_read_b128 v[160:163], v222 offset:17408
	ds_read_b128 v[164:167], v222 offset:18432
	ds_read_b128 v[180:183], v222 offset:19456
	ds_read_b128 v[184:187], v222 offset:20480
	ds_read_b128 v[224:227], v222 offset:21504
	ds_read_b128 v[228:231], v222 offset:22528
	ds_read_b128 v[232:235], v222 offset:23552
	global_load_lds_dwordx4 v0, s[54:55]
	s_add_u32 s76, s54, 0x80
	s_mov_b32 m0, s61
	s_addc_u32 s77, s55, 0
	global_load_lds_dwordx4 v2, s[54:55]
	s_barrier
	s_waitcnt lgkmcnt(0)
	v_mfma_f32_16x16x32_bf16 v[60:63], v[130:133], v[156:159], v[60:63]
	v_mfma_f32_16x16x32_bf16 v[56:59], v[144:147], v[156:159], v[56:59]
	v_mfma_f32_16x16x32_bf16 v[44:47], v[130:133], v[164:167], v[44:47]
	v_mfma_f32_16x16x32_bf16 v[40:43], v[144:147], v[164:167], v[40:43]
	v_mfma_f32_16x16x32_bf16 v[28:31], v[130:133], v[184:187], v[28:31]
	v_mfma_f32_16x16x32_bf16 v[24:27], v[144:147], v[184:187], v[24:27]
	v_mfma_f32_16x16x32_bf16 v[12:15], v[130:133], v[228:231], v[12:15]
	v_mfma_f32_16x16x32_bf16 v[8:11], v[144:147], v[228:231], v[8:11]
	v_mfma_f32_16x16x32_bf16 v[60:63], v[134:137], v[160:163], v[60:63]
	v_mfma_f32_16x16x32_bf16 v[56:59], v[148:151], v[160:163], v[56:59]
	v_mfma_f32_16x16x32_bf16 v[44:47], v[134:137], v[180:183], v[44:47]
	v_mfma_f32_16x16x32_bf16 v[40:43], v[148:151], v[180:183], v[40:43]
	v_mfma_f32_16x16x32_bf16 v[28:31], v[134:137], v[224:227], v[28:31]
	v_mfma_f32_16x16x32_bf16 v[24:27], v[148:151], v[224:227], v[24:27]
	v_mfma_f32_16x16x32_bf16 v[12:15], v[134:137], v[232:235], v[12:15]
	v_mfma_f32_16x16x32_bf16 v[8:11], v[148:151], v[232:235], v[8:11]
	s_barrier
	s_add_i32 m0, s59, 0x14000
	s_add_u32 s74, s52, 0x40000
	s_addc_u32 s75, s53, 0
	global_load_lds_dwordx4 v0, s[74:75]
	s_add_i32 m0, s59, 0x16000
	s_add_u32 s54, s54, 0x40000
	s_addc_u32 s55, s55, 0
	global_load_lds_dwordx4 v2, s[74:75]
	s_waitcnt vmcnt(6)
	s_barrier
;     __device__ __forceinline__ void prep(int pm, int par, LAS unsigned char* lds) const { if (fold) prep_rowstats(stat, pm, par, lds); }
;     __device__ __forceinline__ void prep(int pm, int par, LAS unsigned char* lds) const { if (!ident) prep_rowstats(stat, pm, par, lds); }
;     __device__ __forceinline__ void prep(int pm, int par, LAS unsigned char* lds) const { prep_rowstats(stat, pm, par, lds); }
; #define G_STAGE(bufoff, gbase) do { _Pragma("unroll") for (int _i = 0; _i < 2; ++_i) \
;         __builtin_amdgcn_global_load_lds((const unsigned*)((const char*)(gbase) + voff[_i]), (LAS unsigned*)(lds + (bufoff) + ldsw + _i * 8192), 16, 0, 0); } while (0)
; #define G_WAIT_V(n) asm volatile("s_waitcnt vmcnt(" #n ")" ::: "memory")
; #define G_BAR __builtin_amdgcn_s_barrier()
; template <class Epi>
; __device__ __forceinline__ void gemm_phase(LAS unsigned char* lds, const bf16_t* Ag, const bf16_t* Btg, const int K, const int nM, const int nN, const Epi& E) {
;     ...
;         for (int t = 0; t < nt; t += 2) {
;             const bool last = (t == nt - 2);
;             const char* a1 = cA + (size_t)(t + 1) * kstep;
;             const char* a2 = last ? nA : cA + (size_t)(t + 2) * kstep; const char* b2 = last ? nB : cB + (size_t)(t + 2) * kstep;
;             const char* a3 = a2 + kstep; const char* b3 = b2 + kstep;
;             if (last && has_next && pmn != pm) E.prep(pmn, par ^ 1, lds);
;             G_LDB(B0, 0, 0); G_SCHED; G_LDA(At, 0, 0); G_STAGE(G_SA(1, 1), a1 + hstep);
;             G_WAIT_L(8); G_BAR; G_WAIT_L(0); G_MMA(0, 0, At, B0); G_BAR; G_SCHED;
;             G_LDB(B1, 0, 1); G_STAGE(G_SB(0, 0), b2);
;             G_BAR; G_WAIT_L(0); G_MMA(0, 1, At, B1); G_BAR;
;             G_LDA(At, 0, 1); G_STAGE(G_SA(0, 0), a2);
;             G_BAR; G_WAIT_L(0); G_MMA(1, 0, At, B0); G_BAR; G_SCHED;
;             G_STAGE(G_SB(0, 1), b2 + hstep);
;             G_WAIT_V(6); G_BAR; G_MMA(1, 1, At, B1); G_BAR;
;             G_LDB(B0, 1, 0); G_SCHED; G_LDA(At, 1, 0); G_STAGE(G_SA(0, 1), a2 + hstep);
;             G_WAIT_L(8); G_BAR; G_WAIT_L(0); G_MMA(0, 0, At, B0); G_BAR; G_SCHED;
;             G_LDB(B1, 1, 1); G_STAGE(G_SB(1, 0), b3);
;             G_BAR; G_WAIT_L(0); G_MMA(0, 1, At, B1); G_BAR;
;             G_LDA(At, 1, 1); G_STAGE(G_SA(1, 0), a3);
;             G_BAR; G_WAIT_L(0); G_MMA(1, 0, At, B0); G_BAR; G_SCHED;
;             G_STAGE(G_SB(1, 1), b3 + hstep);
	v_mfma_f32_16x16x32_bf16 v[68:71], v[236:239], v[156:159], v[68:71]
	v_mfma_f32_16x16x32_bf16 v[64:67], v[244:247], v[156:159], v[64:67]
	v_mfma_f32_16x16x32_bf16 v[52:55], v[236:239], v[164:167], v[52:55]
	v_mfma_f32_16x16x32_bf16 v[48:51], v[244:247], v[164:167], v[48:51]
	v_mfma_f32_16x16x32_bf16 v[36:39], v[236:239], v[184:187], v[36:39]
	v_mfma_f32_16x16x32_bf16 v[32:35], v[244:247], v[184:187], v[32:35]
	v_mfma_f32_16x16x32_bf16 v[20:23], v[236:239], v[228:231], v[20:23]
	v_mfma_f32_16x16x32_bf16 v[16:19], v[244:247], v[228:231], v[16:19]
	v_mfma_f32_16x16x32_bf16 v[68:71], v[240:243], v[160:163], v[68:71]
	v_mfma_f32_16x16x32_bf16 v[64:67], v[248:251], v[160:163], v[64:67]
	v_mfma_f32_16x16x32_bf16 v[52:55], v[240:243], v[180:183], v[52:55]
	v_mfma_f32_16x16x32_bf16 v[48:51], v[248:251], v[180:183], v[48:51]
	v_mfma_f32_16x16x32_bf16 v[36:39], v[240:243], v[224:227], v[36:39]
	v_mfma_f32_16x16x32_bf16 v[32:35], v[248:251], v[224:227], v[32:35]
	v_mfma_f32_16x16x32_bf16 v[20:23], v[240:243], v[232:235], v[20:23]
	v_mfma_f32_16x16x32_bf16 v[16:19], v[248:251], v[232:235], v[16:19]
	s_barrier
	ds_read_b128 v[130:133], v217 offset:32768
	ds_read_b128 v[134:137], v217 offset:33792
	ds_read_b128 v[144:147], v217 offset:34816
	ds_read_b128 v[148:151], v217 offset:35840
	s_mov_b32 m0, s62
	ds_read_b128 v[156:159], v222 offset:32768
	ds_read_b128 v[160:163], v222 offset:33792
	ds_read_b128 v[164:167], v222 offset:34816
	ds_read_b128 v[180:183], v222 offset:35840
	ds_read_b128 v[184:187], v222 offset:36864
	ds_read_b128 v[224:227], v222 offset:37888
	ds_read_b128 v[228:231], v222 offset:38912
	global_load_lds_dwordx4 v0, s[54:55]
	s_mov_b32 m0, s63
	ds_read_b128 v[232:235], v222 offset:39936
	global_load_lds_dwordx4 v2, s[54:55]
	s_waitcnt lgkmcnt(8)
	s_barrier
	s_waitcnt lgkmcnt(0)
	v_mfma_f32_16x16x32_bf16 v[152:155], v[130:133], v[156:159], v[152:155]
	v_mfma_f32_16x16x32_bf16 v[138:141], v[144:147], v[156:159], v[138:141]
	v_mfma_f32_16x16x32_bf16 v[116:119], v[130:133], v[164:167], v[116:119]
	v_mfma_f32_16x16x32_bf16 v[112:115], v[144:147], v[164:167], v[112:115]
	v_mfma_f32_16x16x32_bf16 v[100:103], v[130:133], v[184:187], v[100:103]
	v_mfma_f32_16x16x32_bf16 v[96:99], v[144:147], v[184:187], v[96:99]
	v_mfma_f32_16x16x32_bf16 v[84:87], v[130:133], v[228:231], v[84:87]
	v_mfma_f32_16x16x32_bf16 v[80:83], v[144:147], v[228:231], v[80:83]
	v_mfma_f32_16x16x32_bf16 v[152:155], v[134:137], v[160:163], v[152:155]
	v_mfma_f32_16x16x32_bf16 v[140:143], v[148:151], v[160:163], v[138:141]
	v_mfma_f32_16x16x32_bf16 v[116:119], v[134:137], v[180:183], v[116:119]
	v_mfma_f32_16x16x32_bf16 v[112:115], v[148:151], v[180:183], v[112:115]
	v_mfma_f32_16x16x32_bf16 v[100:103], v[134:137], v[224:227], v[100:103]
	v_mfma_f32_16x16x32_bf16 v[96:99], v[148:151], v[224:227], v[96:99]
	v_mfma_f32_16x16x32_bf16 v[84:87], v[134:137], v[232:235], v[84:87]
	v_mfma_f32_16x16x32_bf16 v[80:83], v[148:151], v[232:235], v[80:83]
	s_barrier
	s_add_i32 m0, s59, 0x18000
	ds_read_b128 v[236:239], v217 offset:49152
	ds_read_b128 v[240:243], v217 offset:50176
	ds_read_b128 v[244:247], v217 offset:51200
	s_add_u32 s98, s52, 0x80
	s_addc_u32 s99, s53, 0
	global_load_lds_dwordx4 v0, s[98:99]
	s_add_i32 m0, s59, 0x1a000
	ds_read_b128 v[248:251], v217 offset:52224
	global_load_lds_dwordx4 v2, s[98:99]
	s_barrier
	s_waitcnt lgkmcnt(0)
	v_mfma_f32_16x16x32_bf16 v[124:127], v[236:239], v[156:159], v[124:127]
	v_mfma_f32_16x16x32_bf16 v[120:123], v[244:247], v[156:159], v[120:123]
	v_mfma_f32_16x16x32_bf16 v[108:111], v[236:239], v[164:167], v[108:111]
	v_mfma_f32_16x16x32_bf16 v[104:107], v[244:247], v[164:167], v[104:107]
	v_mfma_f32_16x16x32_bf16 v[92:95], v[236:239], v[184:187], v[92:95]
	v_mfma_f32_16x16x32_bf16 v[88:91], v[244:247], v[184:187], v[88:91]
	v_mfma_f32_16x16x32_bf16 v[76:79], v[236:239], v[228:231], v[76:79]
	v_mfma_f32_16x16x32_bf16 v[72:75], v[244:247], v[228:231], v[72:75]
	v_mfma_f32_16x16x32_bf16 v[124:127], v[240:243], v[160:163], v[124:127]
	v_mfma_f32_16x16x32_bf16 v[120:123], v[248:251], v[160:163], v[120:123]
	v_mfma_f32_16x16x32_bf16 v[108:111], v[240:243], v[180:183], v[108:111]
	v_mfma_f32_16x16x32_bf16 v[104:107], v[248:251], v[180:183], v[104:107]
	v_mfma_f32_16x16x32_bf16 v[92:95], v[240:243], v[224:227], v[92:95]
	v_mfma_f32_16x16x32_bf16 v[88:91], v[248:251], v[224:227], v[88:91]
	v_mfma_f32_16x16x32_bf16 v[76:79], v[240:243], v[232:235], v[76:79]
	v_mfma_f32_16x16x32_bf16 v[72:75], v[248:251], v[232:235], v[72:75]
	s_mov_b32 m0, s64
	s_barrier
	ds_read_b128 v[156:159], v222 offset:49152
	ds_read_b128 v[160:163], v222 offset:50176
	ds_read_b128 v[164:167], v222 offset:51200
	ds_read_b128 v[180:183], v222 offset:52224
	ds_read_b128 v[184:187], v222 offset:53248
	ds_read_b128 v[224:227], v222 offset:54272
	ds_read_b128 v[228:231], v222 offset:55296
	global_load_lds_dwordx4 v0, s[76:77]
	s_mov_b32 m0, s65
	ds_read_b128 v[232:235], v222 offset:56320
	global_load_lds_dwordx4 v2, s[76:77]
	s_barrier
	s_waitcnt lgkmcnt(0)
	v_mfma_f32_16x16x32_bf16 v[60:63], v[130:133], v[156:159], v[60:63]
	v_mfma_f32_16x16x32_bf16 v[56:59], v[144:147], v[156:159], v[56:59]
	v_mfma_f32_16x16x32_bf16 v[44:47], v[130:133], v[164:167], v[44:47]
	v_mfma_f32_16x16x32_bf16 v[40:43], v[144:147], v[164:167], v[40:43]
	v_mfma_f32_16x16x32_bf16 v[28:31], v[130:133], v[184:187], v[28:31]
	v_mfma_f32_16x16x32_bf16 v[24:27], v[144:147], v[184:187], v[24:27]
	v_mfma_f32_16x16x32_bf16 v[12:15], v[130:133], v[228:231], v[12:15]
	v_mfma_f32_16x16x32_bf16 v[8:11], v[144:147], v[228:231], v[8:11]
	v_mfma_f32_16x16x32_bf16 v[60:63], v[134:137], v[160:163], v[60:63]
	v_mfma_f32_16x16x32_bf16 v[56:59], v[148:151], v[160:163], v[56:59]
	v_mfma_f32_16x16x32_bf16 v[44:47], v[134:137], v[180:183], v[44:47]
	v_mfma_f32_16x16x32_bf16 v[40:43], v[148:151], v[180:183], v[40:43]
	v_mfma_f32_16x16x32_bf16 v[28:31], v[134:137], v[224:227], v[28:31]
	v_mfma_f32_16x16x32_bf16 v[24:27], v[148:151], v[224:227], v[24:27]
	v_mfma_f32_16x16x32_bf16 v[12:15], v[134:137], v[232:235], v[12:15]
	v_mfma_f32_16x16x32_bf16 v[8:11], v[148:151], v[232:235], v[8:11]
	s_barrier
	s_add_i32 m0, s59, 0x1c000
	s_add_u32 s52, s52, 0x40080
	s_addc_u32 s53, s53, 0
	global_load_lds_dwordx4 v0, s[52:53]
	s_add_i32 m0, s59, 0x1e000
	s_add_i32 s72, s72, 2
	global_load_lds_dwordx4 v2, s[52:53]
	s_add_u32 s70, s70, 0x100
	s_addc_u32 s71, s71, 0
	s_add_u32 s50, s50, 0x100
	s_addc_u32 s51, s51, 0
	s_cmp_gt_u32 s72, 13
	s_cbranch_scc1 .LrotX_848
	s_cmp_lg_u32 s72, 12
	s_cselect_b64 s[52:53], -1, 0
	s_add_u32 s26, s50, 0xfffc0080
	s_addc_u32 s54, s51, -1
	s_and_b64 s[52:53], s[52:53], exec
	s_cselect_b32 s55, s54, s25
	s_cselect_b32 s54, s26, s24
	s_cselect_b32 s53, s71, s14
	s_cselect_b32 s52, s70, s15
